# SwiGLU epilogues (phases 1,10): packed f32 mul/add, saddr stores, fewer VALU instrs; same math order
# baseline (speedup 1.0000x reference)
; __device__ __forceinline__ unsigned cvt_pk_bf16(float lo, float hi) { unsigned r; asm volatile("v_cvt_pk_bf16_f32 %0, %1, %2" : "=v"(r) : "v"(lo), "v"(hi)); return r; }
;     __device__ __forceinline__ void operator()(const f32x4 (&acc)[2][2][4][2], const Unit& u, int wr, int wc, int fr, int fq) const {
;         const int row0 = u.pm * BM + wr * 64 + fr, col0 = (u.pn * BM + wc * 32) / 2 + 4 * fq;
; #pragma unroll
;         for (int ai = 0; ai < 2; ++ai)
; #pragma unroll
;             for (int m = 0; m < 4; ++m) { bf16_t* rowp = O + (size_t)(row0 + ai * HALF + m * 16) * ldc + col0;
; #pragma unroll
;                 for (int bj = 0; bj < 2; ++bj) { const f32x4 g = acc[ai][bj][m][0], up = acc[ai][bj][m][1];
;                     float a[4];
; #pragma unroll
;                     for (int e = 0; e < 4; ++e) a[e] = g[e] * __builtin_amdgcn_rcpf(1.f + __expf(-g[e])) * up[e];
;                     u32x2 w; w.x = cvt_pk_bf16(a[0], a[1]); w.y = cvt_pk_bf16(a[2], a[3]);
;                     *(u32x2*)(rowp + bj * (HALF / 2)) = w; } }
.LBB0_99:
	s_lshl_b32 s15, s62, 8
	s_or_b32 s15, s15, s55
	s_ashr_i32 s15, s15, 1
	v_or_b32_e32 v146, s15, v150
	v_lshl_add_u32 v154, s26, 8, v148
	v_mov_b32_e32 v158, 0xbfb8aa3b
	v_mov_b32_e32 v159, 0xbfb8aa3b
	v_mul_u32_u24_e32 v168, 0x2c00, v154
	v_lshl_add_u32 v168, v146, 1, v168
	v_pk_mul_f32 v[160:161], v[124:125], v[158:159] op_sel_hi:[1,0]
	v_pk_mul_f32 v[162:163], v[126:127], v[158:159] op_sel_hi:[1,0]
	v_exp_f32_e32 v160, v160
	v_exp_f32_e32 v161, v161
	v_exp_f32_e32 v162, v162
	v_exp_f32_e32 v163, v163
	v_pk_add_f32 v[160:161], v[160:161], 1.0 op_sel_hi:[1,0]
	v_pk_add_f32 v[162:163], v[162:163], 1.0 op_sel_hi:[1,0]
	v_rcp_f32_e32 v160, v160
	v_rcp_f32_e32 v161, v161
	v_rcp_f32_e32 v162, v162
	v_rcp_f32_e32 v163, v163
	v_pk_mul_f32 v[164:165], v[116:117], v[158:159] op_sel_hi:[1,0]
	v_pk_mul_f32 v[166:167], v[118:119], v[158:159] op_sel_hi:[1,0]
	v_exp_f32_e32 v164, v164
	v_exp_f32_e32 v165, v165
	v_exp_f32_e32 v166, v166
	v_exp_f32_e32 v167, v167
	v_pk_mul_f32 v[124:125], v[124:125], v[160:161]
	v_pk_mul_f32 v[126:127], v[126:127], v[162:163]
	v_pk_mul_f32 v[120:121], v[120:121], v[124:125]
	v_pk_mul_f32 v[122:123], v[122:123], v[126:127]
	v_cvt_pk_bf16_f32 v120, v120, v121
	v_cvt_pk_bf16_f32 v121, v122, v123
	global_store_dwordx2 v168, v[120:121], s[34:35]
	v_pk_add_f32 v[164:165], v[164:165], 1.0 op_sel_hi:[1,0]
	v_pk_add_f32 v[166:167], v[166:167], 1.0 op_sel_hi:[1,0]
	v_rcp_f32_e32 v164, v164
	v_rcp_f32_e32 v165, v165
	v_rcp_f32_e32 v166, v166
	v_rcp_f32_e32 v167, v167
	v_pk_mul_f32 v[160:161], v[108:109], v[158:159] op_sel_hi:[1,0]
	v_pk_mul_f32 v[162:163], v[110:111], v[158:159] op_sel_hi:[1,0]
	v_exp_f32_e32 v160, v160
	v_exp_f32_e32 v161, v161
	v_exp_f32_e32 v162, v162
	v_exp_f32_e32 v163, v163
	v_pk_mul_f32 v[116:117], v[116:117], v[164:165]
	v_pk_mul_f32 v[118:119], v[118:119], v[166:167]
	v_pk_mul_f32 v[112:113], v[112:113], v[116:117]
	v_pk_mul_f32 v[114:115], v[114:115], v[118:119]
	v_cvt_pk_bf16_f32 v112, v112, v113
	v_cvt_pk_bf16_f32 v113, v114, v115
	global_store_dwordx2 v168, v[112:113], s[34:35] offset:128
	v_pk_add_f32 v[160:161], v[160:161], 1.0 op_sel_hi:[1,0]
	v_pk_add_f32 v[162:163], v[162:163], 1.0 op_sel_hi:[1,0]
	v_rcp_f32_e32 v160, v160
	v_rcp_f32_e32 v161, v161
	v_rcp_f32_e32 v162, v162
	v_rcp_f32_e32 v163, v163
	v_pk_mul_f32 v[164:165], v[100:101], v[158:159] op_sel_hi:[1,0]
	v_pk_mul_f32 v[166:167], v[102:103], v[158:159] op_sel_hi:[1,0]
	v_exp_f32_e32 v164, v164
	v_exp_f32_e32 v165, v165
	v_exp_f32_e32 v166, v166
	v_exp_f32_e32 v167, v167
	v_add_u32_e32 v169, 0x2c000, v168
	v_pk_mul_f32 v[108:109], v[108:109], v[160:161]
	v_pk_mul_f32 v[110:111], v[110:111], v[162:163]
	v_pk_mul_f32 v[104:105], v[104:105], v[108:109]
	v_pk_mul_f32 v[106:107], v[106:107], v[110:111]
	v_cvt_pk_bf16_f32 v104, v104, v105
	v_cvt_pk_bf16_f32 v105, v106, v107
	global_store_dwordx2 v169, v[104:105], s[34:35]
	v_pk_add_f32 v[164:165], v[164:165], 1.0 op_sel_hi:[1,0]
	v_pk_add_f32 v[166:167], v[166:167], 1.0 op_sel_hi:[1,0]
	v_rcp_f32_e32 v164, v164
	v_rcp_f32_e32 v165, v165
	v_rcp_f32_e32 v166, v166
	v_rcp_f32_e32 v167, v167
	v_pk_mul_f32 v[160:161], v[92:93], v[158:159] op_sel_hi:[1,0]
	v_pk_mul_f32 v[162:163], v[94:95], v[158:159] op_sel_hi:[1,0]
	v_exp_f32_e32 v160, v160
	v_exp_f32_e32 v161, v161
	v_exp_f32_e32 v162, v162
	v_exp_f32_e32 v163, v163
	v_pk_mul_f32 v[100:101], v[100:101], v[164:165]
	v_pk_mul_f32 v[102:103], v[102:103], v[166:167]
	v_pk_mul_f32 v[96:97], v[96:97], v[100:101]
	v_pk_mul_f32 v[98:99], v[98:99], v[102:103]
	v_cvt_pk_bf16_f32 v96, v96, v97
	v_cvt_pk_bf16_f32 v97, v98, v99
	global_store_dwordx2 v169, v[96:97], s[34:35] offset:128
	v_pk_add_f32 v[160:161], v[160:161], 1.0 op_sel_hi:[1,0]
	v_pk_add_f32 v[162:163], v[162:163], 1.0 op_sel_hi:[1,0]
	v_rcp_f32_e32 v160, v160
	v_rcp_f32_e32 v161, v161
	v_rcp_f32_e32 v162, v162
	v_rcp_f32_e32 v163, v163
	v_pk_mul_f32 v[164:165], v[84:85], v[158:159] op_sel_hi:[1,0]
	v_pk_mul_f32 v[166:167], v[86:87], v[158:159] op_sel_hi:[1,0]
	v_exp_f32_e32 v164, v164
	v_exp_f32_e32 v165, v165
	v_exp_f32_e32 v166, v166
	v_exp_f32_e32 v167, v167
	v_add_u32_e32 v170, 0x58000, v168
	v_pk_mul_f32 v[92:93], v[92:93], v[160:161]
	v_pk_mul_f32 v[94:95], v[94:95], v[162:163]
	v_pk_mul_f32 v[88:89], v[88:89], v[92:93]
	v_pk_mul_f32 v[90:91], v[90:91], v[94:95]
	v_cvt_pk_bf16_f32 v88, v88, v89
	v_cvt_pk_bf16_f32 v89, v90, v91
	global_store_dwordx2 v170, v[88:89], s[34:35]
	v_pk_add_f32 v[164:165], v[164:165], 1.0 op_sel_hi:[1,0]
	v_pk_add_f32 v[166:167], v[166:167], 1.0 op_sel_hi:[1,0]
	v_rcp_f32_e32 v164, v164
	v_rcp_f32_e32 v165, v165
	v_rcp_f32_e32 v166, v166
	v_rcp_f32_e32 v167, v167
	v_pk_mul_f32 v[160:161], v[76:77], v[158:159] op_sel_hi:[1,0]
	v_pk_mul_f32 v[162:163], v[78:79], v[158:159] op_sel_hi:[1,0]
	v_exp_f32_e32 v160, v160
	v_exp_f32_e32 v161, v161
	v_exp_f32_e32 v162, v162
	v_exp_f32_e32 v163, v163
	v_pk_mul_f32 v[84:85], v[84:85], v[164:165]
	v_pk_mul_f32 v[86:87], v[86:87], v[166:167]
	v_pk_mul_f32 v[80:81], v[80:81], v[84:85]
	v_pk_mul_f32 v[82:83], v[82:83], v[86:87]
	v_cvt_pk_bf16_f32 v80, v80, v81
	v_cvt_pk_bf16_f32 v81, v82, v83
	global_store_dwordx2 v170, v[80:81], s[34:35] offset:128
	v_pk_add_f32 v[160:161], v[160:161], 1.0 op_sel_hi:[1,0]
	v_pk_add_f32 v[162:163], v[162:163], 1.0 op_sel_hi:[1,0]
	v_rcp_f32_e32 v160, v160
	v_rcp_f32_e32 v161, v161
	v_rcp_f32_e32 v162, v162
	v_rcp_f32_e32 v163, v163
	v_pk_mul_f32 v[164:165], v[68:69], v[158:159] op_sel_hi:[1,0]
	v_pk_mul_f32 v[166:167], v[70:71], v[158:159] op_sel_hi:[1,0]
	v_exp_f32_e32 v164, v164
	v_exp_f32_e32 v165, v165
	v_exp_f32_e32 v166, v166
	v_exp_f32_e32 v167, v167
	v_add_u32_e32 v169, 0x84000, v168
; __device__ __forceinline__ unsigned cvt_pk_bf16(float lo, float hi) { unsigned r; asm volatile("v_cvt_pk_bf16_f32 %0, %1, %2" : "=v"(r) : "v"(lo), "v"(hi)); return r; }
;     __device__ __forceinline__ void operator()(const f32x4 (&acc)[2][2][4][2], const Unit& u, int wr, int wc, int fr, int fq) const {
;         const int row0 = u.pm * BM + wr * 64 + fr, col0 = (u.pn * BM + wc * 32) / 2 + 4 * fq;
; #pragma unroll
;         for (int ai = 0; ai < 2; ++ai)
; #pragma unroll
;             for (int m = 0; m < 4; ++m) { bf16_t* rowp = O + (size_t)(row0 + ai * HALF + m * 16) * ldc + col0;
; #pragma unroll
;                 for (int bj = 0; bj < 2; ++bj) { const f32x4 g = acc[ai][bj][m][0], up = acc[ai][bj][m][1];
;                     float a[4];
; #pragma unroll
;                     for (int e = 0; e < 4; ++e) a[e] = g[e] * __builtin_amdgcn_rcpf(1.f + __expf(-g[e])) * up[e];
;                     u32x2 w; w.x = cvt_pk_bf16(a[0], a[1]); w.y = cvt_pk_bf16(a[2], a[3]);
;                     *(u32x2*)(rowp + bj * (HALF / 2)) = w; } }
	v_pk_mul_f32 v[76:77], v[76:77], v[160:161]
	v_pk_mul_f32 v[78:79], v[78:79], v[162:163]
	v_pk_mul_f32 v[72:73], v[72:73], v[76:77]
	v_pk_mul_f32 v[74:75], v[74:75], v[78:79]
	v_cvt_pk_bf16_f32 v72, v72, v73
	v_cvt_pk_bf16_f32 v73, v74, v75
	global_store_dwordx2 v169, v[72:73], s[34:35]
	v_pk_add_f32 v[164:165], v[164:165], 1.0 op_sel_hi:[1,0]
	v_pk_add_f32 v[166:167], v[166:167], 1.0 op_sel_hi:[1,0]
	v_rcp_f32_e32 v164, v164
	v_rcp_f32_e32 v165, v165
	v_rcp_f32_e32 v166, v166
	v_rcp_f32_e32 v167, v167
	v_pk_mul_f32 v[160:161], v[60:61], v[158:159] op_sel_hi:[1,0]
	v_pk_mul_f32 v[162:163], v[62:63], v[158:159] op_sel_hi:[1,0]
	v_exp_f32_e32 v160, v160
	v_exp_f32_e32 v161, v161
	v_exp_f32_e32 v162, v162
	v_exp_f32_e32 v163, v163
	v_pk_mul_f32 v[68:69], v[68:69], v[164:165]
	v_pk_mul_f32 v[70:71], v[70:71], v[166:167]
	v_pk_mul_f32 v[64:65], v[64:65], v[68:69]
	v_pk_mul_f32 v[66:67], v[66:67], v[70:71]
	v_cvt_pk_bf16_f32 v64, v64, v65
	v_cvt_pk_bf16_f32 v65, v66, v67
	global_store_dwordx2 v169, v[64:65], s[34:35] offset:128
	v_pk_add_f32 v[160:161], v[160:161], 1.0 op_sel_hi:[1,0]
	v_pk_add_f32 v[162:163], v[162:163], 1.0 op_sel_hi:[1,0]
	v_rcp_f32_e32 v160, v160
	v_rcp_f32_e32 v161, v161
	v_rcp_f32_e32 v162, v162
	v_rcp_f32_e32 v163, v163
	v_pk_mul_f32 v[164:165], v[52:53], v[158:159] op_sel_hi:[1,0]
	v_pk_mul_f32 v[166:167], v[54:55], v[158:159] op_sel_hi:[1,0]
	v_exp_f32_e32 v164, v164
	v_exp_f32_e32 v165, v165
	v_exp_f32_e32 v166, v166
	v_exp_f32_e32 v167, v167
	v_add_u32_e32 v170, 0x160000, v168
	v_pk_mul_f32 v[60:61], v[60:61], v[160:161]
	v_pk_mul_f32 v[62:63], v[62:63], v[162:163]
	v_pk_mul_f32 v[56:57], v[56:57], v[60:61]
	v_pk_mul_f32 v[58:59], v[58:59], v[62:63]
	v_cvt_pk_bf16_f32 v56, v56, v57
	v_cvt_pk_bf16_f32 v57, v58, v59
	global_store_dwordx2 v170, v[56:57], s[34:35]
	v_pk_add_f32 v[164:165], v[164:165], 1.0 op_sel_hi:[1,0]
	v_pk_add_f32 v[166:167], v[166:167], 1.0 op_sel_hi:[1,0]
	v_rcp_f32_e32 v164, v164
	v_rcp_f32_e32 v165, v165
	v_rcp_f32_e32 v166, v166
	v_rcp_f32_e32 v167, v167
	v_pk_mul_f32 v[160:161], v[44:45], v[158:159] op_sel_hi:[1,0]
	v_pk_mul_f32 v[162:163], v[46:47], v[158:159] op_sel_hi:[1,0]
	v_exp_f32_e32 v160, v160
	v_exp_f32_e32 v161, v161
	v_exp_f32_e32 v162, v162
	v_exp_f32_e32 v163, v163
	v_pk_mul_f32 v[52:53], v[52:53], v[164:165]
	v_pk_mul_f32 v[54:55], v[54:55], v[166:167]
	v_pk_mul_f32 v[48:49], v[48:49], v[52:53]
	v_pk_mul_f32 v[50:51], v[50:51], v[54:55]
	v_cvt_pk_bf16_f32 v48, v48, v49
	v_cvt_pk_bf16_f32 v49, v50, v51
	global_store_dwordx2 v170, v[48:49], s[34:35] offset:128
	v_pk_add_f32 v[160:161], v[160:161], 1.0 op_sel_hi:[1,0]
	v_pk_add_f32 v[162:163], v[162:163], 1.0 op_sel_hi:[1,0]
	v_rcp_f32_e32 v160, v160
	v_rcp_f32_e32 v161, v161
	v_rcp_f32_e32 v162, v162
	v_rcp_f32_e32 v163, v163
	v_pk_mul_f32 v[164:165], v[36:37], v[158:159] op_sel_hi:[1,0]
	v_pk_mul_f32 v[166:167], v[38:39], v[158:159] op_sel_hi:[1,0]
	v_exp_f32_e32 v164, v164
	v_exp_f32_e32 v165, v165
	v_exp_f32_e32 v166, v166
	v_exp_f32_e32 v167, v167
	v_add_u32_e32 v169, 0x18c000, v168
	v_pk_mul_f32 v[44:45], v[44:45], v[160:161]
	v_pk_mul_f32 v[46:47], v[46:47], v[162:163]
	v_pk_mul_f32 v[40:41], v[40:41], v[44:45]
	v_pk_mul_f32 v[42:43], v[42:43], v[46:47]
	v_cvt_pk_bf16_f32 v40, v40, v41
	v_cvt_pk_bf16_f32 v41, v42, v43
	global_store_dwordx2 v169, v[40:41], s[34:35]
	v_pk_add_f32 v[164:165], v[164:165], 1.0 op_sel_hi:[1,0]
	v_pk_add_f32 v[166:167], v[166:167], 1.0 op_sel_hi:[1,0]
	v_rcp_f32_e32 v164, v164
	v_rcp_f32_e32 v165, v165
	v_rcp_f32_e32 v166, v166
	v_rcp_f32_e32 v167, v167
	v_pk_mul_f32 v[160:161], v[28:29], v[158:159] op_sel_hi:[1,0]
	v_pk_mul_f32 v[162:163], v[30:31], v[158:159] op_sel_hi:[1,0]
	v_exp_f32_e32 v160, v160
	v_exp_f32_e32 v161, v161
	v_exp_f32_e32 v162, v162
	v_exp_f32_e32 v163, v163
	v_pk_mul_f32 v[36:37], v[36:37], v[164:165]
	v_pk_mul_f32 v[38:39], v[38:39], v[166:167]
	v_pk_mul_f32 v[32:33], v[32:33], v[36:37]
	v_pk_mul_f32 v[34:35], v[34:35], v[38:39]
	v_cvt_pk_bf16_f32 v32, v32, v33
	v_cvt_pk_bf16_f32 v33, v34, v35
	global_store_dwordx2 v169, v[32:33], s[34:35] offset:128
	v_pk_add_f32 v[160:161], v[160:161], 1.0 op_sel_hi:[1,0]
	v_pk_add_f32 v[162:163], v[162:163], 1.0 op_sel_hi:[1,0]
	v_rcp_f32_e32 v160, v160
	v_rcp_f32_e32 v161, v161
	v_rcp_f32_e32 v162, v162
	v_rcp_f32_e32 v163, v163
	v_pk_mul_f32 v[164:165], v[20:21], v[158:159] op_sel_hi:[1,0]
	v_pk_mul_f32 v[166:167], v[22:23], v[158:159] op_sel_hi:[1,0]
	v_exp_f32_e32 v164, v164
	v_exp_f32_e32 v165, v165
	v_exp_f32_e32 v166, v166
	v_exp_f32_e32 v167, v167
	v_add_u32_e32 v170, 0x1b8000, v168
	v_pk_mul_f32 v[28:29], v[28:29], v[160:161]
	v_pk_mul_f32 v[30:31], v[30:31], v[162:163]
	v_pk_mul_f32 v[24:25], v[24:25], v[28:29]
	v_pk_mul_f32 v[26:27], v[26:27], v[30:31]
	v_cvt_pk_bf16_f32 v24, v24, v25
	v_cvt_pk_bf16_f32 v25, v26, v27
	global_store_dwordx2 v170, v[24:25], s[34:35]
	v_pk_add_f32 v[164:165], v[164:165], 1.0 op_sel_hi:[1,0]
	v_pk_add_f32 v[166:167], v[166:167], 1.0 op_sel_hi:[1,0]
	v_rcp_f32_e32 v164, v164
	v_rcp_f32_e32 v165, v165
	v_rcp_f32_e32 v166, v166
	v_rcp_f32_e32 v167, v167
	v_pk_mul_f32 v[160:161], v[12:13], v[158:159] op_sel_hi:[1,0]
	v_pk_mul_f32 v[162:163], v[14:15], v[158:159] op_sel_hi:[1,0]
	v_exp_f32_e32 v160, v160
	v_exp_f32_e32 v161, v161
	v_exp_f32_e32 v162, v162
	v_exp_f32_e32 v163, v163
	v_pk_mul_f32 v[20:21], v[20:21], v[164:165]
	v_pk_mul_f32 v[22:23], v[22:23], v[166:167]
	v_pk_mul_f32 v[16:17], v[16:17], v[20:21]
	v_pk_mul_f32 v[18:19], v[18:19], v[22:23]
	v_cvt_pk_bf16_f32 v16, v16, v17
	v_cvt_pk_bf16_f32 v17, v18, v19
	global_store_dwordx2 v170, v[16:17], s[34:35] offset:128
	v_pk_add_f32 v[160:161], v[160:161], 1.0 op_sel_hi:[1,0]
	v_pk_add_f32 v[162:163], v[162:163], 1.0 op_sel_hi:[1,0]
	v_rcp_f32_e32 v160, v160
	v_rcp_f32_e32 v161, v161
	v_rcp_f32_e32 v162, v162
	v_rcp_f32_e32 v163, v163
	v_pk_mul_f32 v[164:165], v[4:5], v[158:159] op_sel_hi:[1,0]
	v_pk_mul_f32 v[166:167], v[6:7], v[158:159] op_sel_hi:[1,0]
	v_exp_f32_e32 v164, v164
	v_exp_f32_e32 v165, v165
	v_exp_f32_e32 v166, v166
	v_exp_f32_e32 v167, v167
	v_add_u32_e32 v169, 0x1e4000, v168
	v_pk_mul_f32 v[12:13], v[12:13], v[160:161]
	v_pk_mul_f32 v[14:15], v[14:15], v[162:163]
	v_pk_mul_f32 v[8:9], v[8:9], v[12:13]
	v_pk_mul_f32 v[10:11], v[10:11], v[14:15]
	v_cvt_pk_bf16_f32 v8, v8, v9
	v_cvt_pk_bf16_f32 v9, v10, v11
	global_store_dwordx2 v169, v[8:9], s[34:35]
	v_pk_add_f32 v[164:165], v[164:165], 1.0 op_sel_hi:[1,0]
	v_pk_add_f32 v[166:167], v[166:167], 1.0 op_sel_hi:[1,0]
	v_rcp_f32_e32 v164, v164
	v_rcp_f32_e32 v165, v165
	v_rcp_f32_e32 v166, v166
	v_rcp_f32_e32 v167, v167
	v_pk_mul_f32 v[4:5], v[4:5], v[164:165]
	v_pk_mul_f32 v[6:7], v[6:7], v[166:167]
	v_pk_mul_f32 v[0:1], v[0:1], v[4:5]
	v_pk_mul_f32 v[2:3], v[2:3], v[6:7]
	v_cvt_pk_bf16_f32 v0, v0, v1
	v_cvt_pk_bf16_f32 v1, v2, v3
	s_andn2_b64 vcc, exec, s[4:5]
	s_mov_b64 s[4:5], -1
	global_store_dwordx2 v169, v[0:1], s[34:35] offset:128
	s_cbranch_vccnz .LBB0_92
	s_andn2_b64 vcc, exec, s[8:9]
	s_cbranch_vccnz .LBB0_91
	s_barrier
	s_branch .LBB0_91

; __device__ __forceinline__ unsigned cvt_pk_bf16(float lo, float hi) { unsigned r; asm volatile("v_cvt_pk_bf16_f32 %0, %1, %2" : "=v"(r) : "v"(lo), "v"(hi)); return r; }
;     __device__ __forceinline__ void operator()(const f32x4 (&acc)[2][2][4][2], const Unit& u, int wr, int wc, int fr, int fq) const {
;         const int row0 = u.pm * BM + wr * 64 + fr, col0 = (u.pn * BM + wc * 32) / 2 + 4 * fq;
; #pragma unroll
;         for (int ai = 0; ai < 2; ++ai)
; #pragma unroll
;             for (int m = 0; m < 4; ++m) { bf16_t* rowp = O + (size_t)(row0 + ai * HALF + m * 16) * ldc + col0;
; #pragma unroll
;                 for (int bj = 0; bj < 2; ++bj) { const f32x4 g = acc[ai][bj][m][0], up = acc[ai][bj][m][1];
;                     float a[4];
; #pragma unroll
;                     for (int e = 0; e < 4; ++e) a[e] = g[e] * __builtin_amdgcn_rcpf(1.f + __expf(-g[e])) * up[e];
;                     u32x2 w; w.x = cvt_pk_bf16(a[0], a[1]); w.y = cvt_pk_bf16(a[2], a[3]);
;                     *(u32x2*)(rowp + bj * (HALF / 2)) = w; } }
.LBB0_1459:
	s_lshl_b32 s15, s60, 8
	s_or_b32 s15, s15, s53
	s_ashr_i32 s15, s15, 1
	v_or_b32_e32 v146, s15, v150
	v_lshl_add_u32 v154, s24, 8, v148
	v_mov_b32_e32 v158, 0xbfb8aa3b
	v_mov_b32_e32 v159, 0xbfb8aa3b
	v_mul_u32_u24_e32 v168, 0x2c00, v154
	v_lshl_add_u32 v168, v146, 1, v168
	v_pk_mul_f32 v[160:161], v[124:125], v[158:159] op_sel_hi:[1,0]
	v_pk_mul_f32 v[162:163], v[126:127], v[158:159] op_sel_hi:[1,0]
	v_exp_f32_e32 v160, v160
	v_exp_f32_e32 v161, v161
	v_exp_f32_e32 v162, v162
	v_exp_f32_e32 v163, v163
	v_pk_add_f32 v[160:161], v[160:161], 1.0 op_sel_hi:[1,0]
	v_pk_add_f32 v[162:163], v[162:163], 1.0 op_sel_hi:[1,0]
	v_rcp_f32_e32 v160, v160
	v_rcp_f32_e32 v161, v161
	v_rcp_f32_e32 v162, v162
	v_rcp_f32_e32 v163, v163
	v_pk_mul_f32 v[164:165], v[116:117], v[158:159] op_sel_hi:[1,0]
	v_pk_mul_f32 v[166:167], v[118:119], v[158:159] op_sel_hi:[1,0]
	v_exp_f32_e32 v164, v164
	v_exp_f32_e32 v165, v165
	v_exp_f32_e32 v166, v166
	v_exp_f32_e32 v167, v167
	v_pk_mul_f32 v[124:125], v[124:125], v[160:161]
	v_pk_mul_f32 v[126:127], v[126:127], v[162:163]
	v_pk_mul_f32 v[120:121], v[120:121], v[124:125]
	v_pk_mul_f32 v[122:123], v[122:123], v[126:127]
	v_cvt_pk_bf16_f32 v120, v120, v121
	v_cvt_pk_bf16_f32 v121, v122, v123
	global_store_dwordx2 v168, v[120:121], s[34:35]
	v_pk_add_f32 v[164:165], v[164:165], 1.0 op_sel_hi:[1,0]
	v_pk_add_f32 v[166:167], v[166:167], 1.0 op_sel_hi:[1,0]
	v_rcp_f32_e32 v164, v164
	v_rcp_f32_e32 v165, v165
	v_rcp_f32_e32 v166, v166
	v_rcp_f32_e32 v167, v167
	v_pk_mul_f32 v[160:161], v[108:109], v[158:159] op_sel_hi:[1,0]
	v_pk_mul_f32 v[162:163], v[110:111], v[158:159] op_sel_hi:[1,0]
	v_exp_f32_e32 v160, v160
	v_exp_f32_e32 v161, v161
	v_exp_f32_e32 v162, v162
	v_exp_f32_e32 v163, v163
	v_pk_mul_f32 v[116:117], v[116:117], v[164:165]
	v_pk_mul_f32 v[118:119], v[118:119], v[166:167]
	v_pk_mul_f32 v[112:113], v[112:113], v[116:117]
	v_pk_mul_f32 v[114:115], v[114:115], v[118:119]
	v_cvt_pk_bf16_f32 v112, v112, v113
	v_cvt_pk_bf16_f32 v113, v114, v115
	global_store_dwordx2 v168, v[112:113], s[34:35] offset:128
	v_pk_add_f32 v[160:161], v[160:161], 1.0 op_sel_hi:[1,0]
	v_pk_add_f32 v[162:163], v[162:163], 1.0 op_sel_hi:[1,0]
	v_rcp_f32_e32 v160, v160
	v_rcp_f32_e32 v161, v161
	v_rcp_f32_e32 v162, v162
	v_rcp_f32_e32 v163, v163
	v_pk_mul_f32 v[164:165], v[100:101], v[158:159] op_sel_hi:[1,0]
	v_pk_mul_f32 v[166:167], v[102:103], v[158:159] op_sel_hi:[1,0]
	v_exp_f32_e32 v164, v164
	v_exp_f32_e32 v165, v165
	v_exp_f32_e32 v166, v166
	v_exp_f32_e32 v167, v167
	v_add_u32_e32 v169, 0x2c000, v168
	v_pk_mul_f32 v[108:109], v[108:109], v[160:161]
	v_pk_mul_f32 v[110:111], v[110:111], v[162:163]
	v_pk_mul_f32 v[104:105], v[104:105], v[108:109]
	v_pk_mul_f32 v[106:107], v[106:107], v[110:111]
	v_cvt_pk_bf16_f32 v104, v104, v105
	v_cvt_pk_bf16_f32 v105, v106, v107
	global_store_dwordx2 v169, v[104:105], s[34:35]
	v_pk_add_f32 v[164:165], v[164:165], 1.0 op_sel_hi:[1,0]
	v_pk_add_f32 v[166:167], v[166:167], 1.0 op_sel_hi:[1,0]
	v_rcp_f32_e32 v164, v164
	v_rcp_f32_e32 v165, v165
	v_rcp_f32_e32 v166, v166
	v_rcp_f32_e32 v167, v167
	v_pk_mul_f32 v[160:161], v[92:93], v[158:159] op_sel_hi:[1,0]
	v_pk_mul_f32 v[162:163], v[94:95], v[158:159] op_sel_hi:[1,0]
	v_exp_f32_e32 v160, v160
	v_exp_f32_e32 v161, v161
	v_exp_f32_e32 v162, v162
	v_exp_f32_e32 v163, v163
	v_pk_mul_f32 v[100:101], v[100:101], v[164:165]
	v_pk_mul_f32 v[102:103], v[102:103], v[166:167]
	v_pk_mul_f32 v[96:97], v[96:97], v[100:101]
	v_pk_mul_f32 v[98:99], v[98:99], v[102:103]
	v_cvt_pk_bf16_f32 v96, v96, v97
	v_cvt_pk_bf16_f32 v97, v98, v99
	global_store_dwordx2 v169, v[96:97], s[34:35] offset:128
	v_pk_add_f32 v[160:161], v[160:161], 1.0 op_sel_hi:[1,0]
	v_pk_add_f32 v[162:163], v[162:163], 1.0 op_sel_hi:[1,0]
	v_rcp_f32_e32 v160, v160
	v_rcp_f32_e32 v161, v161
	v_rcp_f32_e32 v162, v162
	v_rcp_f32_e32 v163, v163
	v_pk_mul_f32 v[164:165], v[84:85], v[158:159] op_sel_hi:[1,0]
	v_pk_mul_f32 v[166:167], v[86:87], v[158:159] op_sel_hi:[1,0]
	v_exp_f32_e32 v164, v164
	v_exp_f32_e32 v165, v165
	v_exp_f32_e32 v166, v166
	v_exp_f32_e32 v167, v167
	v_add_u32_e32 v170, 0x58000, v168
	v_pk_mul_f32 v[92:93], v[92:93], v[160:161]
	v_pk_mul_f32 v[94:95], v[94:95], v[162:163]
	v_pk_mul_f32 v[88:89], v[88:89], v[92:93]
	v_pk_mul_f32 v[90:91], v[90:91], v[94:95]
	v_cvt_pk_bf16_f32 v88, v88, v89
	v_cvt_pk_bf16_f32 v89, v90, v91
	global_store_dwordx2 v170, v[88:89], s[34:35]
	v_pk_add_f32 v[164:165], v[164:165], 1.0 op_sel_hi:[1,0]
	v_pk_add_f32 v[166:167], v[166:167], 1.0 op_sel_hi:[1,0]
	v_rcp_f32_e32 v164, v164
	v_rcp_f32_e32 v165, v165
	v_rcp_f32_e32 v166, v166
	v_rcp_f32_e32 v167, v167
	v_pk_mul_f32 v[160:161], v[76:77], v[158:159] op_sel_hi:[1,0]
	v_pk_mul_f32 v[162:163], v[78:79], v[158:159] op_sel_hi:[1,0]
	v_exp_f32_e32 v160, v160
	v_exp_f32_e32 v161, v161
	v_exp_f32_e32 v162, v162
	v_exp_f32_e32 v163, v163
	v_pk_mul_f32 v[84:85], v[84:85], v[164:165]
	v_pk_mul_f32 v[86:87], v[86:87], v[166:167]
	v_pk_mul_f32 v[80:81], v[80:81], v[84:85]
	v_pk_mul_f32 v[82:83], v[82:83], v[86:87]
	v_cvt_pk_bf16_f32 v80, v80, v81
	v_cvt_pk_bf16_f32 v81, v82, v83
	global_store_dwordx2 v170, v[80:81], s[34:35] offset:128
	v_pk_add_f32 v[160:161], v[160:161], 1.0 op_sel_hi:[1,0]
	v_pk_add_f32 v[162:163], v[162:163], 1.0 op_sel_hi:[1,0]
	v_rcp_f32_e32 v160, v160
	v_rcp_f32_e32 v161, v161
	v_rcp_f32_e32 v162, v162
	v_rcp_f32_e32 v163, v163
	v_pk_mul_f32 v[164:165], v[68:69], v[158:159] op_sel_hi:[1,0]
	v_pk_mul_f32 v[166:167], v[70:71], v[158:159] op_sel_hi:[1,0]
	v_exp_f32_e32 v164, v164
	v_exp_f32_e32 v165, v165
	v_exp_f32_e32 v166, v166
	v_exp_f32_e32 v167, v167
	v_add_u32_e32 v169, 0x84000, v168
; __device__ __forceinline__ unsigned cvt_pk_bf16(float lo, float hi) { unsigned r; asm volatile("v_cvt_pk_bf16_f32 %0, %1, %2" : "=v"(r) : "v"(lo), "v"(hi)); return r; }
;     __device__ __forceinline__ void operator()(const f32x4 (&acc)[2][2][4][2], const Unit& u, int wr, int wc, int fr, int fq) const {
;         const int row0 = u.pm * BM + wr * 64 + fr, col0 = (u.pn * BM + wc * 32) / 2 + 4 * fq;
; #pragma unroll
;         for (int ai = 0; ai < 2; ++ai)
; #pragma unroll
;             for (int m = 0; m < 4; ++m) { bf16_t* rowp = O + (size_t)(row0 + ai * HALF + m * 16) * ldc + col0;
; #pragma unroll
;                 for (int bj = 0; bj < 2; ++bj) { const f32x4 g = acc[ai][bj][m][0], up = acc[ai][bj][m][1];
;                     float a[4];
; #pragma unroll
;                     for (int e = 0; e < 4; ++e) a[e] = g[e] * __builtin_amdgcn_rcpf(1.f + __expf(-g[e])) * up[e];
;                     u32x2 w; w.x = cvt_pk_bf16(a[0], a[1]); w.y = cvt_pk_bf16(a[2], a[3]);
;                     *(u32x2*)(rowp + bj * (HALF / 2)) = w; } }
	v_pk_mul_f32 v[76:77], v[76:77], v[160:161]
	v_pk_mul_f32 v[78:79], v[78:79], v[162:163]
	v_pk_mul_f32 v[72:73], v[72:73], v[76:77]
	v_pk_mul_f32 v[74:75], v[74:75], v[78:79]
	v_cvt_pk_bf16_f32 v72, v72, v73
	v_cvt_pk_bf16_f32 v73, v74, v75
	global_store_dwordx2 v169, v[72:73], s[34:35]
	v_pk_add_f32 v[164:165], v[164:165], 1.0 op_sel_hi:[1,0]
	v_pk_add_f32 v[166:167], v[166:167], 1.0 op_sel_hi:[1,0]
	v_rcp_f32_e32 v164, v164
	v_rcp_f32_e32 v165, v165
	v_rcp_f32_e32 v166, v166
	v_rcp_f32_e32 v167, v167
	v_pk_mul_f32 v[160:161], v[60:61], v[158:159] op_sel_hi:[1,0]
	v_pk_mul_f32 v[162:163], v[62:63], v[158:159] op_sel_hi:[1,0]
	v_exp_f32_e32 v160, v160
	v_exp_f32_e32 v161, v161
	v_exp_f32_e32 v162, v162
	v_exp_f32_e32 v163, v163
	v_pk_mul_f32 v[68:69], v[68:69], v[164:165]
	v_pk_mul_f32 v[70:71], v[70:71], v[166:167]
	v_pk_mul_f32 v[64:65], v[64:65], v[68:69]
	v_pk_mul_f32 v[66:67], v[66:67], v[70:71]
	v_cvt_pk_bf16_f32 v64, v64, v65
	v_cvt_pk_bf16_f32 v65, v66, v67
	global_store_dwordx2 v169, v[64:65], s[34:35] offset:128
	v_pk_add_f32 v[160:161], v[160:161], 1.0 op_sel_hi:[1,0]
	v_pk_add_f32 v[162:163], v[162:163], 1.0 op_sel_hi:[1,0]
	v_rcp_f32_e32 v160, v160
	v_rcp_f32_e32 v161, v161
	v_rcp_f32_e32 v162, v162
	v_rcp_f32_e32 v163, v163
	v_pk_mul_f32 v[164:165], v[52:53], v[158:159] op_sel_hi:[1,0]
	v_pk_mul_f32 v[166:167], v[54:55], v[158:159] op_sel_hi:[1,0]
	v_exp_f32_e32 v164, v164
	v_exp_f32_e32 v165, v165
	v_exp_f32_e32 v166, v166
	v_exp_f32_e32 v167, v167
	v_add_u32_e32 v170, 0x160000, v168
	v_pk_mul_f32 v[60:61], v[60:61], v[160:161]
	v_pk_mul_f32 v[62:63], v[62:63], v[162:163]
	v_pk_mul_f32 v[56:57], v[56:57], v[60:61]
	v_pk_mul_f32 v[58:59], v[58:59], v[62:63]
	v_cvt_pk_bf16_f32 v56, v56, v57
	v_cvt_pk_bf16_f32 v57, v58, v59
	global_store_dwordx2 v170, v[56:57], s[34:35]
	v_pk_add_f32 v[164:165], v[164:165], 1.0 op_sel_hi:[1,0]
	v_pk_add_f32 v[166:167], v[166:167], 1.0 op_sel_hi:[1,0]
	v_rcp_f32_e32 v164, v164
	v_rcp_f32_e32 v165, v165
	v_rcp_f32_e32 v166, v166
	v_rcp_f32_e32 v167, v167
	v_pk_mul_f32 v[160:161], v[44:45], v[158:159] op_sel_hi:[1,0]
	v_pk_mul_f32 v[162:163], v[46:47], v[158:159] op_sel_hi:[1,0]
	v_exp_f32_e32 v160, v160
	v_exp_f32_e32 v161, v161
	v_exp_f32_e32 v162, v162
	v_exp_f32_e32 v163, v163
	v_pk_mul_f32 v[52:53], v[52:53], v[164:165]
	v_pk_mul_f32 v[54:55], v[54:55], v[166:167]
	v_pk_mul_f32 v[48:49], v[48:49], v[52:53]
	v_pk_mul_f32 v[50:51], v[50:51], v[54:55]
	v_cvt_pk_bf16_f32 v48, v48, v49
	v_cvt_pk_bf16_f32 v49, v50, v51
	global_store_dwordx2 v170, v[48:49], s[34:35] offset:128
	v_pk_add_f32 v[160:161], v[160:161], 1.0 op_sel_hi:[1,0]
	v_pk_add_f32 v[162:163], v[162:163], 1.0 op_sel_hi:[1,0]
	v_rcp_f32_e32 v160, v160
	v_rcp_f32_e32 v161, v161
	v_rcp_f32_e32 v162, v162
	v_rcp_f32_e32 v163, v163
	v_pk_mul_f32 v[164:165], v[36:37], v[158:159] op_sel_hi:[1,0]
	v_pk_mul_f32 v[166:167], v[38:39], v[158:159] op_sel_hi:[1,0]
	v_exp_f32_e32 v164, v164
	v_exp_f32_e32 v165, v165
	v_exp_f32_e32 v166, v166
	v_exp_f32_e32 v167, v167
	v_add_u32_e32 v169, 0x18c000, v168
	v_pk_mul_f32 v[44:45], v[44:45], v[160:161]
	v_pk_mul_f32 v[46:47], v[46:47], v[162:163]
	v_pk_mul_f32 v[40:41], v[40:41], v[44:45]
	v_pk_mul_f32 v[42:43], v[42:43], v[46:47]
	v_cvt_pk_bf16_f32 v40, v40, v41
	v_cvt_pk_bf16_f32 v41, v42, v43
	global_store_dwordx2 v169, v[40:41], s[34:35]
	v_pk_add_f32 v[164:165], v[164:165], 1.0 op_sel_hi:[1,0]
	v_pk_add_f32 v[166:167], v[166:167], 1.0 op_sel_hi:[1,0]
	v_rcp_f32_e32 v164, v164
	v_rcp_f32_e32 v165, v165
	v_rcp_f32_e32 v166, v166
	v_rcp_f32_e32 v167, v167
	v_pk_mul_f32 v[160:161], v[28:29], v[158:159] op_sel_hi:[1,0]
	v_pk_mul_f32 v[162:163], v[30:31], v[158:159] op_sel_hi:[1,0]
	v_exp_f32_e32 v160, v160
	v_exp_f32_e32 v161, v161
	v_exp_f32_e32 v162, v162
	v_exp_f32_e32 v163, v163
	v_pk_mul_f32 v[36:37], v[36:37], v[164:165]
	v_pk_mul_f32 v[38:39], v[38:39], v[166:167]
	v_pk_mul_f32 v[32:33], v[32:33], v[36:37]
	v_pk_mul_f32 v[34:35], v[34:35], v[38:39]
	v_cvt_pk_bf16_f32 v32, v32, v33
	v_cvt_pk_bf16_f32 v33, v34, v35
	global_store_dwordx2 v169, v[32:33], s[34:35] offset:128
	v_pk_add_f32 v[160:161], v[160:161], 1.0 op_sel_hi:[1,0]
	v_pk_add_f32 v[162:163], v[162:163], 1.0 op_sel_hi:[1,0]
	v_rcp_f32_e32 v160, v160
	v_rcp_f32_e32 v161, v161
	v_rcp_f32_e32 v162, v162
	v_rcp_f32_e32 v163, v163
	v_pk_mul_f32 v[164:165], v[20:21], v[158:159] op_sel_hi:[1,0]
	v_pk_mul_f32 v[166:167], v[22:23], v[158:159] op_sel_hi:[1,0]
	v_exp_f32_e32 v164, v164
	v_exp_f32_e32 v165, v165
	v_exp_f32_e32 v166, v166
	v_exp_f32_e32 v167, v167
	v_add_u32_e32 v170, 0x1b8000, v168
	v_pk_mul_f32 v[28:29], v[28:29], v[160:161]
	v_pk_mul_f32 v[30:31], v[30:31], v[162:163]
	v_pk_mul_f32 v[24:25], v[24:25], v[28:29]
	v_pk_mul_f32 v[26:27], v[26:27], v[30:31]
	v_cvt_pk_bf16_f32 v24, v24, v25
	v_cvt_pk_bf16_f32 v25, v26, v27
	global_store_dwordx2 v170, v[24:25], s[34:35]
	v_pk_add_f32 v[164:165], v[164:165], 1.0 op_sel_hi:[1,0]
	v_pk_add_f32 v[166:167], v[166:167], 1.0 op_sel_hi:[1,0]
	v_rcp_f32_e32 v164, v164
	v_rcp_f32_e32 v165, v165
	v_rcp_f32_e32 v166, v166
	v_rcp_f32_e32 v167, v167
	v_pk_mul_f32 v[160:161], v[12:13], v[158:159] op_sel_hi:[1,0]
	v_pk_mul_f32 v[162:163], v[14:15], v[158:159] op_sel_hi:[1,0]
	v_exp_f32_e32 v160, v160
	v_exp_f32_e32 v161, v161
	v_exp_f32_e32 v162, v162
	v_exp_f32_e32 v163, v163
	v_pk_mul_f32 v[20:21], v[20:21], v[164:165]
	v_pk_mul_f32 v[22:23], v[22:23], v[166:167]
	v_pk_mul_f32 v[16:17], v[16:17], v[20:21]
	v_pk_mul_f32 v[18:19], v[18:19], v[22:23]
	v_cvt_pk_bf16_f32 v16, v16, v17
	v_cvt_pk_bf16_f32 v17, v18, v19
	global_store_dwordx2 v170, v[16:17], s[34:35] offset:128
	v_pk_add_f32 v[160:161], v[160:161], 1.0 op_sel_hi:[1,0]
	v_pk_add_f32 v[162:163], v[162:163], 1.0 op_sel_hi:[1,0]
	v_rcp_f32_e32 v160, v160
	v_rcp_f32_e32 v161, v161
	v_rcp_f32_e32 v162, v162
	v_rcp_f32_e32 v163, v163
	v_pk_mul_f32 v[164:165], v[4:5], v[158:159] op_sel_hi:[1,0]
	v_pk_mul_f32 v[166:167], v[6:7], v[158:159] op_sel_hi:[1,0]
	v_exp_f32_e32 v164, v164
	v_exp_f32_e32 v165, v165
	v_exp_f32_e32 v166, v166
	v_exp_f32_e32 v167, v167
	v_add_u32_e32 v169, 0x1e4000, v168
	v_pk_mul_f32 v[12:13], v[12:13], v[160:161]
	v_pk_mul_f32 v[14:15], v[14:15], v[162:163]
	v_pk_mul_f32 v[8:9], v[8:9], v[12:13]
	v_pk_mul_f32 v[10:11], v[10:11], v[14:15]
	v_cvt_pk_bf16_f32 v8, v8, v9
	v_cvt_pk_bf16_f32 v9, v10, v11
	global_store_dwordx2 v169, v[8:9], s[34:35]
	v_pk_add_f32 v[164:165], v[164:165], 1.0 op_sel_hi:[1,0]
	v_pk_add_f32 v[166:167], v[166:167], 1.0 op_sel_hi:[1,0]
	v_rcp_f32_e32 v164, v164
	v_rcp_f32_e32 v165, v165
	v_rcp_f32_e32 v166, v166
	v_rcp_f32_e32 v167, v167
	v_pk_mul_f32 v[4:5], v[4:5], v[164:165]
	v_pk_mul_f32 v[6:7], v[6:7], v[166:167]
	v_pk_mul_f32 v[0:1], v[0:1], v[4:5]
	v_pk_mul_f32 v[2:3], v[2:3], v[6:7]
	v_cvt_pk_bf16_f32 v0, v0, v1
	v_cvt_pk_bf16_f32 v1, v2, v3
	s_andn2_b64 vcc, exec, s[4:5]
	s_mov_b64 s[4:5], -1
	global_store_dwordx2 v169, v[0:1], s[34:35] offset:128
	s_cbranch_vccnz .LBB0_1452
	s_andn2_b64 vcc, exec, s[8:9]
	s_cbranch_vccnz .LBB0_1451
	s_barrier
	s_branch .LBB0_1451
